# v27 + nt (streaming) policy on the read-once loads of the norm and final-norm phases
# speedup vs baseline: 1.0038x; 1.0038x over previous
; __device__ __forceinline__ void final_norm_phase(const _Float16* xh, float* out, const float* g, int rows) {
;     ...
;         for (int r = 0; r < 4; ++r) { const f16x4* xr = (const f16x4*)(xh + (size_t)(m0 + r) * DM) + lane;
; #pragma unroll
;             for (int j = 0; j < 4; ++j) v[r][j] = __builtin_convertvector(xr[64 * j], f32x4); }
; #pragma unroll
;         for (int r = 0; r < 4; ++r) { float s = 0.f;
; #pragma unroll
;             for (int j = 0; j < 4; ++j) s += (v[r][j].x * v[r][j].x + v[r][j].y * v[r][j].y) + (v[r][j].z * v[r][j].z + v[r][j].w * v[r][j].w);
.LBB0_184:
	v_add_co_u32_e32 v26, vcc, 0xfffff000, v24
	v_add_u32_e32 v20, s30, v20
	s_nop 0
	v_addc_co_u32_e32 v27, vcc, -1, v25, vcc
	global_load_dwordx2 v[16:17], v[26:27], off offset:-3584 nt
	global_load_dwordx2 v[28:29], v[26:27], off offset:-2048 nt
	global_load_dwordx2 v[34:35], v[24:25], off offset:-1536 nt
	global_load_dwordx2 v[38:39], v[24:25], off offset:-1024 nt
	global_load_dwordx2 v[46:47], v[24:25], off offset:-512 nt
	global_load_dwordx2 v[92:93], v[24:25], off nt
	s_waitcnt vmcnt(5)
	v_cvt_f32_f16_e32 v82, v16
	v_cvt_f32_f16_sdwa v83, v16 dst_sel:DWORD dst_unused:UNUSED_PAD src0_sel:WORD_1
	v_cvt_f32_f16_e32 v84, v17
	v_cvt_f32_f16_sdwa v85, v17 dst_sel:DWORD dst_unused:UNUSED_PAD src0_sel:WORD_1
	global_load_dwordx2 v[16:17], v[26:27], off offset:-3072 nt
	s_waitcnt vmcnt(5)
	v_cvt_f32_f16_sdwa v81, v28 dst_sel:DWORD dst_unused:UNUSED_PAD src0_sel:WORD_1
	v_cvt_f32_f16_e32 v80, v28
	s_waitcnt vmcnt(3)
	v_cvt_f32_f16_sdwa v37, v39 dst_sel:DWORD dst_unused:UNUSED_PAD src0_sel:WORD_1
	v_cvt_f32_f16_e32 v36, v39
	s_waitcnt vmcnt(2)
	v_cvt_f32_f16_sdwa v39, v46 dst_sel:DWORD dst_unused:UNUSED_PAD src0_sel:WORD_1
	v_cvt_f32_f16_sdwa v41, v47 dst_sel:DWORD dst_unused:UNUSED_PAD src0_sel:WORD_1
	v_cvt_f32_f16_e32 v40, v47
	v_pk_mul_f32 v[94:95], v[82:83], v[82:83]
	v_mul_f32_e32 v21, v80, v80
	s_waitcnt vmcnt(1)
	v_cvt_f32_f16_sdwa v47, v93 dst_sel:DWORD dst_unused:UNUSED_PAD src0_sel:WORD_1
	v_cvt_f32_f16_sdwa v49, v92 dst_sel:DWORD dst_unused:UNUSED_PAD src0_sel:WORD_1
	v_cvt_f32_f16_e32 v48, v92
	s_waitcnt vmcnt(0)
	v_cvt_f32_f16_e32 v74, v16
	v_cvt_f32_f16_sdwa v75, v16 dst_sel:DWORD dst_unused:UNUSED_PAD src0_sel:WORD_1
	v_cvt_f32_f16_e32 v78, v17
	v_cvt_f32_f16_sdwa v79, v17 dst_sel:DWORD dst_unused:UNUSED_PAD src0_sel:WORD_1
	global_load_dwordx2 v[16:17], v[26:27], off offset:-2560 nt
	s_waitcnt vmcnt(0)
	v_cvt_f32_f16_e32 v18, v16
	v_cvt_f32_f16_sdwa v19, v16 dst_sel:DWORD dst_unused:UNUSED_PAD src0_sel:WORD_1
	v_cvt_f32_f16_e32 v76, v17
	v_cvt_f32_f16_sdwa v77, v17 dst_sel:DWORD dst_unused:UNUSED_PAD src0_sel:WORD_1
	v_cvt_f32_f16_sdwa v17, v29 dst_sel:DWORD dst_unused:UNUSED_PAD src0_sel:WORD_1
	v_cvt_f32_f16_e32 v16, v29
	global_load_dwordx2 v[28:29], v[26:27], off offset:-1536 nt
	s_waitcnt vmcnt(0)
	v_cvt_f32_f16_e32 v60, v28
	v_cvt_f32_f16_sdwa v61, v28 dst_sel:DWORD dst_unused:UNUSED_PAD src0_sel:WORD_1
	v_cvt_f32_f16_e32 v68, v29
	v_cvt_f32_f16_sdwa v69, v29 dst_sel:DWORD dst_unused:UNUSED_PAD src0_sel:WORD_1
	global_load_dwordx2 v[28:29], v[26:27], off offset:-1024 nt
	s_waitcnt vmcnt(0)
	v_cvt_f32_f16_e32 v58, v28
	global_load_dwordx2 v[26:27], v[26:27], off offset:-512 nt
	v_cvt_f32_f16_sdwa v59, v28 dst_sel:DWORD dst_unused:UNUSED_PAD src0_sel:WORD_1
	v_cvt_f32_f16_e32 v66, v29
	v_cvt_f32_f16_sdwa v67, v29 dst_sel:DWORD dst_unused:UNUSED_PAD src0_sel:WORD_1
	v_cvt_f32_f16_sdwa v29, v35 dst_sel:DWORD dst_unused:UNUSED_PAD src0_sel:WORD_1
	v_cvt_f32_f16_e32 v28, v35
	v_cvt_f32_f16_sdwa v35, v38 dst_sel:DWORD dst_unused:UNUSED_PAD src0_sel:WORD_1
	s_waitcnt vmcnt(0)
	v_cvt_f32_f16_e32 v56, v26
	v_cvt_f32_f16_sdwa v57, v26 dst_sel:DWORD dst_unused:UNUSED_PAD src0_sel:WORD_1
	v_cvt_f32_f16_e32 v64, v27
	v_cvt_f32_f16_sdwa v65, v27 dst_sel:DWORD dst_unused:UNUSED_PAD src0_sel:WORD_1
	global_load_dwordx2 v[26:27], v[24:25], off offset:-4096 nt
	s_waitcnt vmcnt(0)
	v_cvt_f32_f16_sdwa v55, v27 dst_sel:DWORD dst_unused:UNUSED_PAD src0_sel:WORD_1
	v_cvt_f32_f16_sdwa v63, v26 dst_sel:DWORD dst_unused:UNUSED_PAD src0_sel:WORD_1
	v_cvt_f32_f16_e32 v54, v27
	v_cvt_f32_f16_e32 v62, v26
	global_load_dwordx2 v[26:27], v[24:25], off offset:-3584 nt
	s_waitcnt vmcnt(0)
	v_cvt_f32_f16_sdwa v71, v26 dst_sel:DWORD dst_unused:UNUSED_PAD src0_sel:WORD_1
	v_cvt_f32_f16_sdwa v73, v27 dst_sel:DWORD dst_unused:UNUSED_PAD src0_sel:WORD_1
	v_cvt_f32_f16_e32 v70, v26
	v_cvt_f32_f16_e32 v72, v27
	global_load_dwordx2 v[26:27], v[24:25], off offset:-3072 nt
	s_waitcnt vmcnt(0)
	v_cvt_f32_f16_sdwa v31, v26 dst_sel:DWORD dst_unused:UNUSED_PAD src0_sel:WORD_1
	v_cvt_f32_f16_sdwa v33, v27 dst_sel:DWORD dst_unused:UNUSED_PAD src0_sel:WORD_1
	v_cvt_f32_f16_e32 v30, v26
	v_cvt_f32_f16_e32 v32, v27
	global_load_dwordx2 v[26:27], v[24:25], off offset:-2560 nt
	s_waitcnt vmcnt(0)
	v_cvt_f32_f16_sdwa v43, v26 dst_sel:DWORD dst_unused:UNUSED_PAD src0_sel:WORD_1
	v_cvt_f32_f16_sdwa v45, v27 dst_sel:DWORD dst_unused:UNUSED_PAD src0_sel:WORD_1
	v_cvt_f32_f16_e32 v42, v26
	v_cvt_f32_f16_e32 v44, v27
	global_load_dwordx2 v[26:27], v[24:25], off offset:-2048 nt
	v_lshl_add_u64 v[24:25], v[24:25], 0, s[68:69]
	s_waitcnt vmcnt(0)
	v_cvt_f32_f16_sdwa v51, v27 dst_sel:DWORD dst_unused:UNUSED_PAD src0_sel:WORD_1
	v_cvt_f32_f16_sdwa v53, v26 dst_sel:DWORD dst_unused:UNUSED_PAD src0_sel:WORD_1
	v_cvt_f32_f16_e32 v50, v27
	v_cvt_f32_f16_e32 v52, v26
	v_cvt_f32_f16_sdwa v27, v34 dst_sel:DWORD dst_unused:UNUSED_PAD src0_sel:WORD_1
	v_cvt_f32_f16_e32 v26, v34
	v_cvt_f32_f16_e32 v34, v38
	v_cvt_f32_f16_e32 v38, v46
	v_cvt_f32_f16_e32 v46, v93
	v_pk_mul_f32 v[92:93], v[84:85], v[84:85]
	s_nop 0
	v_pk_mov_b32 v[96:97], v[94:95], v[92:93] op_sel:[1,0]
	v_mov_b32_e32 v95, v93
	v_pk_add_f32 v[92:93], v[96:97], v[94:95]
	v_pk_mul_f32 v[94:95], v[78:79], v[78:79]
	v_pk_mul_f32 v[96:97], v[74:75], v[74:75]
	v_pk_add_f32 v[92:93], v[92:93], v[92:93] op_sel:[0,1] op_sel_hi:[1,0]
	v_pk_mov_b32 v[98:99], v[96:97], v[94:95] op_sel:[1,0]
	v_mov_b32_e32 v97, v95
	v_pk_add_f32 v[94:95], v[98:99], v[96:97]
	v_mul_f32_e32 v96, v81, v81
	v_pk_add_f32 v[94:95], v[94:95], v[94:95] op_sel:[0,1] op_sel_hi:[1,0]
	v_mov_b32_e32 v93, v21
	v_mov_b32_e32 v95, v96
	v_pk_add_f32 v[92:93], v[92:93], v[94:95]
	v_mul_f32_e32 v94, v19, v19
	v_mul_f32_e32 v97, v16, v16
	v_pk_fma_f32 v[94:95], v[18:19], v[18:19], v[94:95] op_sel_hi:[1,1,0]
	v_mul_f32_e32 v96, v77, v77
	v_mul_f32_e32 v98, v17, v17
	v_mov_b32_e32 v95, v97
	v_pk_fma_f32 v[96:97], v[76:77], v[76:77], v[96:97] op_sel_hi:[1,1,0]
	s_nop 0
	v_mov_b32_e32 v97, v98
	v_pk_add_f32 v[94:95], v[94:95], v[96:97]
	s_nop 0
	v_pk_add_f32 v[92:93], v[92:93], v[94:95]
	s_nop 0
	v_add_f32_e32 v21, v92, v93
	ds_bpermute_b32 v92, v86, v21
	s_waitcnt lgkmcnt(0)
; __device__ __forceinline__ void final_norm_phase(const _Float16* xh, float* out, const float* g, int rows) {
;     ...
;         for (int r = 0; r < 4; ++r) { float s = 0.f;
; #pragma unroll
;             for (int j = 0; j < 4; ++j) s += (v[r][j].x * v[r][j].x + v[r][j].y * v[r][j].y) + (v[r][j].z * v[r][j].z + v[r][j].w * v[r][j].w);
;             const float rstd = 1.0f / sqrtf(wave_sum(s) * (1.0f / DM) + RMS_EPS);
;             f32x4* orow = (f32x4*)(out + (size_t)(m0 + r) * DM) + lane;
; #pragma unroll
;             for (int j = 0; j < 4; ++j) orow[64 * j] = v[r][j] * rstd * gv[j]; }
	v_add_f32_e32 v21, v21, v92
	ds_bpermute_b32 v92, v87, v21
	s_waitcnt lgkmcnt(0)
	v_add_f32_e32 v21, v21, v92
	ds_bpermute_b32 v92, v88, v21
	s_waitcnt lgkmcnt(0)
	v_add_f32_e32 v21, v21, v92
	ds_bpermute_b32 v92, v89, v21
	s_waitcnt lgkmcnt(0)
	v_add_f32_e32 v21, v21, v92
	ds_bpermute_b32 v92, v90, v21
	s_waitcnt lgkmcnt(0)
	v_add_f32_e32 v21, v21, v92
	ds_bpermute_b32 v92, v91, v21
	s_waitcnt lgkmcnt(0)
	v_add_f32_e32 v21, v21, v92
	v_fmamk_f32 v21, v21, 0x3a800000, v195
	v_cmp_gt_f32_e32 vcc, s33, v21
	v_mul_f32_e32 v92, 0x4f800000, v21
	s_nop 0
	v_cndmask_b32_e32 v21, v21, v92, vcc
	v_sqrt_f32_e32 v92, v21
	s_nop 0
	v_add_u32_e32 v93, -1, v92
	v_fma_f32 v94, -v93, v92, v21
	v_cmp_ge_f32_e64 s[0:1], 0, v94
	v_add_u32_e32 v94, 1, v92
	s_nop 0
	v_cndmask_b32_e64 v93, v92, v93, s[0:1]
	v_fma_f32 v92, -v94, v92, v21
	v_cmp_lt_f32_e64 s[0:1], 0, v92
	s_nop 1
	v_cndmask_b32_e64 v92, v93, v94, s[0:1]
	v_mul_f32_e32 v93, 0x37800000, v92
	v_cndmask_b32_e32 v92, v92, v93, vcc
	v_cmp_class_f32_e32 vcc, v21, v197
	s_nop 1
	v_cndmask_b32_e32 v21, v92, v21, vcc
	v_div_scale_f32 v92, s[0:1], v21, v21, 1.0
	v_rcp_f32_e32 v93, v92
	s_movk_i32 s0, 0xd000
	v_fma_f32 v94, -v92, v93, 1.0
	v_fmac_f32_e32 v93, v94, v93
	v_div_scale_f32 v94, vcc, 1.0, v21, 1.0
	v_mul_f32_e32 v95, v94, v93
	v_fma_f32 v96, -v92, v95, v94
	v_fmac_f32_e32 v95, v96, v93
	v_fma_f32 v92, -v92, v95, v94
	v_div_fmas_f32 v92, v92, v93, v95
	v_div_fixup_f32 v92, v92, v21, 1.0
	v_pk_mul_f32 v[82:83], v[92:93], v[82:83] op_sel_hi:[0,1]
	v_pk_mul_f32 v[84:85], v[92:93], v[84:85] op_sel_hi:[0,1]
	v_add_co_u32_e32 v94, vcc, s0, v22
	v_pk_mul_f32 v[84:85], v[2:3], v[84:85]
	v_pk_mul_f32 v[82:83], v[0:1], v[82:83]
	v_addc_co_u32_e32 v95, vcc, -1, v23, vcc
	v_pk_mul_f32 v[74:75], v[92:93], v[74:75] op_sel_hi:[0,1]
	global_store_dwordx4 v[94:95], v[82:85], off offset:-3072 sc1
	v_pk_mul_f32 v[18:19], v[92:93], v[18:19] op_sel_hi:[0,1]
	v_pk_mul_f32 v[16:17], v[92:93], v[16:17] op_sel_hi:[0,1]
	v_pk_mul_f32 v[82:83], v[4:5], v[74:75]
	v_pk_mul_f32 v[74:75], v[92:93], v[76:77] op_sel_hi:[0,1]
	v_pk_mul_f32 v[76:77], v[10:11], v[74:75]
	v_pk_mul_f32 v[74:75], v[8:9], v[18:19]
	global_store_dwordx4 v[94:95], v[74:77], off offset:-1024 sc1
	s_movk_i32 s0, 0xe000
	v_pk_mul_f32 v[18:19], v[14:15], v[16:17]
	v_pk_mul_f32 v[74:75], v[92:93], v[80:81] op_sel_hi:[0,1]
	v_pk_mul_f32 v[16:17], v[12:13], v[74:75]
	v_add_co_u32_e32 v74, vcc, s0, v22
	v_pk_mul_f32 v[78:79], v[92:93], v[78:79] op_sel_hi:[0,1]
	s_nop 0
	v_addc_co_u32_e32 v75, vcc, -1, v23, vcc
	global_store_dwordx4 v[74:75], v[16:19], off offset:-4096 sc1
	v_pk_mul_f32 v[84:85], v[6:7], v[78:79]
	v_mul_f32_e32 v21, v62, v62
	v_pk_mul_f32 v[16:17], v[68:69], v[68:69]
	v_pk_mul_f32 v[18:19], v[60:61], v[60:61]
	global_store_dwordx4 v[94:95], v[82:85], off offset:-2048 sc1
	v_pk_mov_b32 v[76:77], v[18:19], v[16:17] op_sel:[1,0]
	v_mov_b32_e32 v19, v17
	v_pk_add_f32 v[16:17], v[76:77], v[18:19]
	v_pk_mul_f32 v[18:19], v[66:67], v[66:67]
	v_pk_mul_f32 v[76:77], v[58:59], v[58:59]
	v_pk_add_f32 v[16:17], v[16:17], v[16:17] op_sel:[0,1] op_sel_hi:[1,0]
	v_pk_mov_b32 v[78:79], v[76:77], v[18:19] op_sel:[1,0]
	v_mov_b32_e32 v77, v19
	v_pk_add_f32 v[18:19], v[78:79], v[76:77]
	v_mul_f32_e32 v76, v63, v63
	v_pk_add_f32 v[18:19], v[18:19], v[18:19] op_sel:[0,1] op_sel_hi:[1,0]
	v_mov_b32_e32 v17, v21
	v_mov_b32_e32 v19, v76
	v_pk_add_f32 v[16:17], v[16:17], v[18:19]
	v_mul_f32_e32 v18, v57, v57
	v_mul_f32_e32 v77, v54, v54
	v_pk_fma_f32 v[18:19], v[56:57], v[56:57], v[18:19] op_sel_hi:[1,1,0]
	v_mul_f32_e32 v76, v65, v65
	v_mul_f32_e32 v78, v55, v55
	v_mov_b32_e32 v19, v77
	v_pk_fma_f32 v[76:77], v[64:65], v[64:65], v[76:77] op_sel_hi:[1,1,0]
	s_nop 0
	v_mov_b32_e32 v77, v78
	v_pk_add_f32 v[18:19], v[18:19], v[76:77]
	s_nop 0
	v_pk_add_f32 v[16:17], v[16:17], v[18:19]
	s_nop 0
	v_add_f32_e32 v16, v16, v17
	ds_bpermute_b32 v17, v86, v16
	s_waitcnt lgkmcnt(0)
	v_add_f32_e32 v16, v16, v17
	ds_bpermute_b32 v17, v87, v16
	s_waitcnt lgkmcnt(0)
	v_add_f32_e32 v16, v16, v17
	ds_bpermute_b32 v17, v88, v16
	s_waitcnt lgkmcnt(0)
	v_add_f32_e32 v16, v16, v17
	ds_bpermute_b32 v17, v89, v16
	s_waitcnt lgkmcnt(0)
	v_add_f32_e32 v16, v16, v17
	ds_bpermute_b32 v17, v90, v16
	s_waitcnt lgkmcnt(0)
	v_add_f32_e32 v16, v16, v17
	ds_bpermute_b32 v17, v91, v16
	s_waitcnt lgkmcnt(0)
; __device__ __forceinline__ void final_norm_phase(const _Float16* xh, float* out, const float* g, int rows) {
;     ...
;         for (int r = 0; r < 4; ++r) { float s = 0.f;
; #pragma unroll
;             for (int j = 0; j < 4; ++j) s += (v[r][j].x * v[r][j].x + v[r][j].y * v[r][j].y) + (v[r][j].z * v[r][j].z + v[r][j].w * v[r][j].w);
;             const float rstd = 1.0f / sqrtf(wave_sum(s) * (1.0f / DM) + RMS_EPS);
;             f32x4* orow = (f32x4*)(out + (size_t)(m0 + r) * DM) + lane;
; #pragma unroll
;             for (int j = 0; j < 4; ++j) orow[64 * j] = v[r][j] * rstd * gv[j]; }
	v_add_f32_e32 v16, v16, v17
	v_fmamk_f32 v16, v16, 0x3a800000, v195
	v_cmp_gt_f32_e32 vcc, s33, v16
	v_mul_f32_e32 v17, 0x4f800000, v16
	s_nop 0
	v_cndmask_b32_e32 v16, v16, v17, vcc
	v_sqrt_f32_e32 v17, v16
	s_nop 0
	v_add_u32_e32 v18, -1, v17
	v_fma_f32 v19, -v18, v17, v16
	v_cmp_ge_f32_e64 s[0:1], 0, v19
	v_add_u32_e32 v19, 1, v17
	s_nop 0
	v_cndmask_b32_e64 v18, v17, v18, s[0:1]
	v_fma_f32 v17, -v19, v17, v16
	v_cmp_lt_f32_e64 s[0:1], 0, v17
	s_nop 1
	v_cndmask_b32_e64 v17, v18, v19, s[0:1]
	v_mul_f32_e32 v18, 0x37800000, v17
	v_cndmask_b32_e32 v17, v17, v18, vcc
	v_cmp_class_f32_e32 vcc, v16, v197
	s_nop 1
	v_cndmask_b32_e32 v16, v17, v16, vcc
	v_div_scale_f32 v17, s[0:1], v16, v16, 1.0
	v_rcp_f32_e32 v18, v17
	s_nop 0
	v_fma_f32 v19, -v17, v18, 1.0
	v_fmac_f32_e32 v18, v19, v18
	v_div_scale_f32 v19, vcc, 1.0, v16, 1.0
	v_mul_f32_e32 v21, v19, v18
	v_fma_f32 v76, -v17, v21, v19
	v_fmac_f32_e32 v21, v76, v18
	v_fma_f32 v17, -v17, v21, v19
	v_div_fmas_f32 v17, v17, v18, v21
	v_div_fixup_f32 v76, v17, v16, 1.0
	v_pk_mul_f32 v[16:17], v[76:77], v[60:61] op_sel_hi:[0,1]
	v_pk_mul_f32 v[18:19], v[76:77], v[68:69] op_sel_hi:[0,1]
	v_pk_mul_f32 v[18:19], v[2:3], v[18:19]
	v_pk_mul_f32 v[16:17], v[0:1], v[16:17]
	global_store_dwordx4 v[74:75], v[16:19], off offset:-3072 sc1
	v_mul_f32_e32 v21, v52, v52
	s_nop 0
	v_pk_mul_f32 v[16:17], v[76:77], v[58:59] op_sel_hi:[0,1]
	v_pk_mul_f32 v[18:19], v[76:77], v[66:67] op_sel_hi:[0,1]
	v_pk_mul_f32 v[18:19], v[6:7], v[18:19]
	v_pk_mul_f32 v[16:17], v[4:5], v[16:17]
	global_store_dwordx4 v[74:75], v[16:19], off offset:-2048 sc1
	s_nop 1
	v_pk_mul_f32 v[16:17], v[76:77], v[56:57] op_sel_hi:[0,1]
	v_pk_mul_f32 v[18:19], v[76:77], v[64:65] op_sel_hi:[0,1]
	v_pk_mul_f32 v[18:19], v[10:11], v[18:19]
	v_pk_mul_f32 v[16:17], v[8:9], v[16:17]
	global_store_dwordx4 v[74:75], v[16:19], off offset:-1024 sc1
	s_nop 1
	v_pk_mul_f32 v[16:17], v[76:77], v[62:63] op_sel_hi:[0,1]
	v_pk_mul_f32 v[18:19], v[76:77], v[54:55] op_sel_hi:[0,1]
	v_pk_mul_f32 v[18:19], v[14:15], v[18:19]
	v_pk_mul_f32 v[16:17], v[12:13], v[16:17]
	global_store_dwordx4 v[74:75], v[16:19], off sc1
	s_nop 1
	v_pk_mul_f32 v[16:17], v[72:73], v[72:73]
	v_pk_mul_f32 v[18:19], v[70:71], v[70:71]
	s_nop 0
	v_pk_mov_b32 v[54:55], v[18:19], v[16:17] op_sel:[1,0]
	v_mov_b32_e32 v19, v17
	v_pk_add_f32 v[16:17], v[54:55], v[18:19]
	v_pk_mul_f32 v[18:19], v[32:33], v[32:33]
	v_pk_mul_f32 v[54:55], v[30:31], v[30:31]
	v_pk_add_f32 v[16:17], v[16:17], v[16:17] op_sel:[0,1] op_sel_hi:[1,0]
	v_pk_mov_b32 v[56:57], v[54:55], v[18:19] op_sel:[1,0]
	v_mov_b32_e32 v55, v19
	v_pk_add_f32 v[18:19], v[56:57], v[54:55]
	v_mul_f32_e32 v54, v53, v53
	v_pk_add_f32 v[18:19], v[18:19], v[18:19] op_sel:[0,1] op_sel_hi:[1,0]
	v_mov_b32_e32 v17, v21
	v_mov_b32_e32 v19, v54
	v_pk_add_f32 v[16:17], v[16:17], v[18:19]
	v_mul_f32_e32 v18, v43, v43
	v_mul_f32_e32 v55, v50, v50
	v_pk_fma_f32 v[18:19], v[42:43], v[42:43], v[18:19] op_sel_hi:[1,1,0]
	v_mul_f32_e32 v54, v45, v45
	v_mul_f32_e32 v56, v51, v51
	v_mov_b32_e32 v19, v55
	v_pk_fma_f32 v[54:55], v[44:45], v[44:45], v[54:55] op_sel_hi:[1,1,0]
	s_nop 0
	v_mov_b32_e32 v55, v56
	v_pk_add_f32 v[18:19], v[18:19], v[54:55]
	s_nop 0
	v_pk_add_f32 v[16:17], v[16:17], v[18:19]
	s_nop 0
	v_add_f32_e32 v16, v16, v17
	ds_bpermute_b32 v17, v86, v16
	s_waitcnt lgkmcnt(0)
	v_add_f32_e32 v16, v16, v17
	ds_bpermute_b32 v17, v87, v16
	s_waitcnt lgkmcnt(0)
	v_add_f32_e32 v16, v16, v17
	ds_bpermute_b32 v17, v88, v16
	s_waitcnt lgkmcnt(0)
	v_add_f32_e32 v16, v16, v17
	ds_bpermute_b32 v17, v89, v16
	s_waitcnt lgkmcnt(0)
	v_add_f32_e32 v16, v16, v17
	ds_bpermute_b32 v17, v90, v16
	s_waitcnt lgkmcnt(0)
	v_add_f32_e32 v16, v16, v17
	ds_bpermute_b32 v17, v91, v16
	s_waitcnt lgkmcnt(0)
; __device__ __forceinline__ void final_norm_phase(const _Float16* xh, float* out, const float* g, int rows) {
;     ...
;     for (int m0 = gw * 4; m0 < rows; m0 += NGW * 4) {
;         f32x4 v[4][4];
; #pragma unroll
;         for (int r = 0; r < 4; ++r) { const f16x4* xr = (const f16x4*)(xh + (size_t)(m0 + r) * DM) + lane;
; #pragma unroll
;             for (int j = 0; j < 4; ++j) v[r][j] = __builtin_convertvector(xr[64 * j], f32x4); }
; #pragma unroll
;         for (int r = 0; r < 4; ++r) { float s = 0.f;
; #pragma unroll
;             for (int j = 0; j < 4; ++j) s += (v[r][j].x * v[r][j].x + v[r][j].y * v[r][j].y) + (v[r][j].z * v[r][j].z + v[r][j].w * v[r][j].w);
;             const float rstd = 1.0f / sqrtf(wave_sum(s) * (1.0f / DM) + RMS_EPS);
;             f32x4* orow = (f32x4*)(out + (size_t)(m0 + r) * DM) + lane;
; #pragma unroll
;             for (int j = 0; j < 4; ++j) orow[64 * j] = v[r][j] * rstd * gv[j]; }
	v_add_f32_e32 v16, v16, v17
	v_fmamk_f32 v16, v16, 0x3a800000, v195
	v_cmp_gt_f32_e32 vcc, s33, v16
	v_mul_f32_e32 v17, 0x4f800000, v16
	s_nop 0
	v_cndmask_b32_e32 v16, v16, v17, vcc
	v_sqrt_f32_e32 v17, v16
	s_nop 0
	v_add_u32_e32 v18, -1, v17
	v_fma_f32 v19, -v18, v17, v16
	v_cmp_ge_f32_e64 s[0:1], 0, v19
	v_add_u32_e32 v19, 1, v17
	s_nop 0
	v_cndmask_b32_e64 v18, v17, v18, s[0:1]
	v_fma_f32 v17, -v19, v17, v16
	v_cmp_lt_f32_e64 s[0:1], 0, v17
	s_nop 1
	v_cndmask_b32_e64 v17, v18, v19, s[0:1]
	v_mul_f32_e32 v18, 0x37800000, v17
	v_cndmask_b32_e32 v17, v17, v18, vcc
	v_cmp_class_f32_e32 vcc, v16, v197
	s_nop 1
	v_cndmask_b32_e32 v16, v17, v16, vcc
	v_div_scale_f32 v17, s[0:1], v16, v16, 1.0
	v_rcp_f32_e32 v18, v17
	s_movk_i32 s0, 0xf000
	v_fma_f32 v19, -v17, v18, 1.0
	v_fmac_f32_e32 v18, v19, v18
	v_div_scale_f32 v19, vcc, 1.0, v16, 1.0
	v_mul_f32_e32 v21, v19, v18
	v_fma_f32 v54, -v17, v21, v19
	v_fmac_f32_e32 v21, v54, v18
	v_fma_f32 v17, -v17, v21, v19
	v_div_fmas_f32 v17, v17, v18, v21
	v_div_fixup_f32 v16, v17, v16, 1.0
	v_pk_mul_f32 v[18:19], v[16:17], v[70:71] op_sel_hi:[0,1]
	v_pk_mul_f32 v[54:55], v[16:17], v[72:73] op_sel_hi:[0,1]
	v_pk_mul_f32 v[56:57], v[2:3], v[54:55]
	v_pk_mul_f32 v[54:55], v[0:1], v[18:19]
	v_add_co_u32_e32 v18, vcc, s0, v22
	v_pk_mul_f32 v[30:31], v[16:17], v[30:31] op_sel_hi:[0,1]
	v_pk_mul_f32 v[32:33], v[16:17], v[32:33] op_sel_hi:[0,1]
	v_addc_co_u32_e32 v19, vcc, -1, v23, vcc
	v_pk_mul_f32 v[32:33], v[6:7], v[32:33]
	v_pk_mul_f32 v[30:31], v[4:5], v[30:31]
	global_store_dwordx4 v[18:19], v[30:33], off offset:-2048 sc1
	global_store_dwordx4 v[18:19], v[54:57], off offset:-3072 sc1
	v_mul_f32_e32 v21, v48, v48
	v_pk_mul_f32 v[30:31], v[16:17], v[42:43] op_sel_hi:[0,1]
	v_pk_mul_f32 v[32:33], v[16:17], v[44:45] op_sel_hi:[0,1]
	v_pk_mul_f32 v[32:33], v[10:11], v[32:33]
	v_pk_mul_f32 v[30:31], v[8:9], v[30:31]
	global_store_dwordx4 v[18:19], v[30:33], off offset:-1024 sc1
	s_nop 1
	v_pk_mul_f32 v[30:31], v[16:17], v[52:53] op_sel_hi:[0,1]
	v_pk_mul_f32 v[16:17], v[16:17], v[50:51] op_sel_hi:[0,1]
	v_pk_mul_f32 v[18:19], v[14:15], v[16:17]
	v_pk_mul_f32 v[16:17], v[12:13], v[30:31]
	global_store_dwordx4 v[22:23], v[16:19], off offset:-4096 sc1
	s_nop 1
	v_pk_mul_f32 v[16:17], v[28:29], v[28:29]
	v_pk_mul_f32 v[18:19], v[26:27], v[26:27]
	s_nop 0
	v_pk_mov_b32 v[30:31], v[18:19], v[16:17] op_sel:[1,0]
	v_mov_b32_e32 v19, v17
	v_pk_add_f32 v[16:17], v[30:31], v[18:19]
	v_pk_mul_f32 v[18:19], v[36:37], v[36:37]
	v_pk_mul_f32 v[30:31], v[34:35], v[34:35]
	v_pk_add_f32 v[16:17], v[16:17], v[16:17] op_sel:[0,1] op_sel_hi:[1,0]
	v_pk_mov_b32 v[32:33], v[30:31], v[18:19] op_sel:[1,0]
	v_mov_b32_e32 v31, v19
	v_pk_add_f32 v[18:19], v[32:33], v[30:31]
	v_mul_f32_e32 v30, v49, v49
	v_pk_add_f32 v[18:19], v[18:19], v[18:19] op_sel:[0,1] op_sel_hi:[1,0]
	v_mov_b32_e32 v17, v21
	v_mov_b32_e32 v19, v30
	v_pk_add_f32 v[16:17], v[16:17], v[18:19]
	v_mul_f32_e32 v18, v39, v39
	v_mul_f32_e32 v31, v46, v46
	v_pk_fma_f32 v[18:19], v[38:39], v[38:39], v[18:19] op_sel_hi:[1,1,0]
	v_mul_f32_e32 v30, v41, v41
	v_mul_f32_e32 v32, v47, v47
	v_mov_b32_e32 v19, v31
	v_pk_fma_f32 v[30:31], v[40:41], v[40:41], v[30:31] op_sel_hi:[1,1,0]
	s_nop 0
	v_mov_b32_e32 v31, v32
	v_pk_add_f32 v[18:19], v[18:19], v[30:31]
	s_nop 0
	v_pk_add_f32 v[16:17], v[16:17], v[18:19]
	s_nop 0
	v_add_f32_e32 v16, v16, v17
	ds_bpermute_b32 v17, v86, v16
	s_waitcnt lgkmcnt(0)
	v_add_f32_e32 v16, v16, v17
	ds_bpermute_b32 v17, v87, v16
	s_waitcnt lgkmcnt(0)
	v_add_f32_e32 v16, v16, v17
	ds_bpermute_b32 v17, v88, v16
	s_waitcnt lgkmcnt(0)
	v_add_f32_e32 v16, v16, v17
	ds_bpermute_b32 v17, v89, v16
	s_waitcnt lgkmcnt(0)
	v_add_f32_e32 v16, v16, v17
	ds_bpermute_b32 v17, v90, v16
	s_waitcnt lgkmcnt(0)
	v_add_f32_e32 v16, v16, v17
	ds_bpermute_b32 v17, v91, v16
	s_waitcnt lgkmcnt(0)
	v_add_f32_e32 v16, v16, v17
	v_fmamk_f32 v16, v16, 0x3a800000, v195
	v_cmp_gt_f32_e32 vcc, s33, v16
	v_mul_f32_e32 v17, 0x4f800000, v16
	s_nop 0
	v_cndmask_b32_e32 v16, v16, v17, vcc
	v_sqrt_f32_e32 v17, v16
	s_nop 0
	v_add_u32_e32 v18, -1, v17
	v_fma_f32 v19, -v18, v17, v16
	v_cmp_ge_f32_e64 s[0:1], 0, v19
	v_add_u32_e32 v19, 1, v17
	s_nop 0
	v_cndmask_b32_e64 v18, v17, v18, s[0:1]
	v_fma_f32 v17, -v19, v17, v16
	v_cmp_lt_f32_e64 s[0:1], 0, v17
	s_nop 1
	v_cndmask_b32_e64 v17, v18, v19, s[0:1]
	v_mul_f32_e32 v18, 0x37800000, v17
	v_cndmask_b32_e32 v17, v17, v18, vcc
	v_cmp_class_f32_e32 vcc, v16, v197
	s_nop 1
	v_cndmask_b32_e32 v16, v17, v16, vcc
	v_div_scale_f32 v17, s[0:1], v16, v16, 1.0
	v_rcp_f32_e32 v18, v17
	s_nop 0
	v_fma_f32 v19, -v17, v18, 1.0
	v_fmac_f32_e32 v18, v19, v18
	v_div_scale_f32 v19, vcc, 1.0, v16, 1.0
	v_mul_f32_e32 v21, v19, v18
	v_fma_f32 v30, -v17, v21, v19
	v_fmac_f32_e32 v21, v30, v18
	v_fma_f32 v17, -v17, v21, v19
	v_div_fmas_f32 v17, v17, v18, v21
	v_div_fixup_f32 v30, v17, v16, 1.0
	v_pk_mul_f32 v[16:17], v[30:31], v[26:27] op_sel_hi:[0,1]
	v_pk_mul_f32 v[18:19], v[30:31], v[28:29] op_sel_hi:[0,1]
	v_pk_mul_f32 v[18:19], v[2:3], v[18:19]
	v_pk_mul_f32 v[16:17], v[0:1], v[16:17]
	global_store_dwordx4 v[22:23], v[16:19], off offset:-3072 sc1
	v_cmp_le_i32_e32 vcc, s62, v20
	s_or_b64 s[6:7], vcc, s[6:7]
	v_pk_mul_f32 v[16:17], v[30:31], v[34:35] op_sel_hi:[0,1]
	v_pk_mul_f32 v[18:19], v[30:31], v[36:37] op_sel_hi:[0,1]
	v_pk_mul_f32 v[18:19], v[6:7], v[18:19]
	v_pk_mul_f32 v[16:17], v[4:5], v[16:17]
	global_store_dwordx4 v[22:23], v[16:19], off offset:-2048 sc1
	s_nop 1
	v_pk_mul_f32 v[16:17], v[30:31], v[38:39] op_sel_hi:[0,1]
	v_pk_mul_f32 v[18:19], v[30:31], v[40:41] op_sel_hi:[0,1]
	v_pk_mul_f32 v[18:19], v[10:11], v[18:19]
	v_pk_mul_f32 v[16:17], v[8:9], v[16:17]
	global_store_dwordx4 v[22:23], v[16:19], off offset:-1024 sc1
	s_nop 1
	v_pk_mul_f32 v[16:17], v[30:31], v[48:49] op_sel_hi:[0,1]
	v_pk_mul_f32 v[18:19], v[30:31], v[46:47] op_sel_hi:[0,1]
	v_pk_mul_f32 v[18:19], v[14:15], v[18:19]
	v_pk_mul_f32 v[16:17], v[12:13], v[16:17]
	global_store_dwordx4 v[22:23], v[16:19], off sc1
	v_lshl_add_u64 v[22:23], v[22:23], 0, s[70:71]
	s_andn2_b64 exec, exec, s[6:7]
	s_cbranch_execnz .LBB0_184

; __device__ __forceinline__ void norm_phase(const float* x, const _Float16* xh, const float* g, bf16_t* h, int rows) {
;     ...
;         if (xh) {
; #pragma unroll
;             for (int r = 0; r < 4; ++r) { const f16x4* xr = (const f16x4*)(xh + (size_t)(m0 + r) * DM) + lane;
; #pragma unroll
;                 for (int j = 0; j < 4; ++j) v[r][j] = __builtin_convertvector(xr[64 * j], f32x4); }
;         } else {
; #pragma unroll
;             for (int r = 0; r < 4; ++r) { const f32x4* xr = (const f32x4*)(x + (size_t)(m0 + r) * DM) + lane;
; #pragma unroll
;                 for (int j = 0; j < 4; ++j) v[r][j] = xr[64 * j]; }
;         }
.LBB0_523:
	s_andn2_b64 vcc, exec, s[8:9]
	s_cbranch_vccnz .LBB0_525
	v_lshl_add_u64 v[16:17], v[82:83], 0, v[86:87]
	s_movk_i32 s0, 0x1000
	global_load_dwordx2 v[18:19], v[16:17], off nt
	global_load_dwordx2 v[20:21], v[16:17], off offset:512 nt
	global_load_dwordx2 v[22:23], v[16:17], off offset:1024 nt
	global_load_dwordx2 v[24:25], v[16:17], off offset:1536 nt
	global_load_dwordx2 v[26:27], v[16:17], off offset:2048 nt
	global_load_dwordx2 v[28:29], v[16:17], off offset:2560 nt
	global_load_dwordx2 v[30:31], v[16:17], off offset:3072 nt
	global_load_dwordx2 v[32:33], v[16:17], off offset:3584 nt
	v_add_co_u32_e32 v16, vcc, s0, v16
	v_or_b32_e32 v38, 2, v80
	s_nop 0
	v_addc_co_u32_e32 v17, vcc, 0, v17, vcc
	global_load_dwordx2 v[34:35], v[16:17], off nt
	global_load_dwordx2 v[36:37], v[16:17], off offset:512 nt
	global_load_dwordx2 v[92:93], v[16:17], off offset:1024 nt
	global_load_dwordx2 v[104:105], v[16:17], off offset:1536 nt
	global_load_dwordx2 v[106:107], v[16:17], off offset:2048 nt
	global_load_dwordx2 v[108:109], v[16:17], off offset:2560 nt
	global_load_dwordx2 v[110:111], v[16:17], off offset:3072 nt
	global_load_dwordx2 v[112:113], v[16:17], off offset:3584 nt
	v_or_b32_e32 v16, 1, v80
	v_ashrrev_i32_e32 v17, 31, v16
	v_ashrrev_i32_e32 v39, 31, v38
	v_lshlrev_b64 v[96:97], 11, v[16:17]
	v_lshlrev_b64 v[94:95], 11, v[38:39]
	v_or_b32_e32 v114, 3, v80
	v_ashrrev_i32_e32 v115, 31, v114
	s_waitcnt vmcnt(15)
	v_cvt_f32_f16_e32 v76, v18
	v_cvt_f32_f16_e32 v78, v19
	v_cvt_f32_f16_sdwa v79, v19 dst_sel:DWORD dst_unused:UNUSED_PAD src0_sel:WORD_1
	v_cvt_f32_f16_sdwa v77, v18 dst_sel:DWORD dst_unused:UNUSED_PAD src0_sel:WORD_1
	s_waitcnt vmcnt(14)
	v_cvt_f32_f16_e32 v72, v20
	v_cvt_f32_f16_e32 v74, v21
	v_cvt_f32_f16_sdwa v75, v21 dst_sel:DWORD dst_unused:UNUSED_PAD src0_sel:WORD_1
	v_cvt_f32_f16_sdwa v73, v20 dst_sel:DWORD dst_unused:UNUSED_PAD src0_sel:WORD_1
	s_waitcnt vmcnt(13)
	v_cvt_f32_f16_e32 v68, v22
	v_cvt_f32_f16_e32 v70, v23
	v_cvt_f32_f16_sdwa v71, v23 dst_sel:DWORD dst_unused:UNUSED_PAD src0_sel:WORD_1
	v_cvt_f32_f16_sdwa v69, v22 dst_sel:DWORD dst_unused:UNUSED_PAD src0_sel:WORD_1
	s_waitcnt vmcnt(12)
	v_cvt_f32_f16_e32 v64, v24
	v_cvt_f32_f16_e32 v66, v25
	v_cvt_f32_f16_sdwa v67, v25 dst_sel:DWORD dst_unused:UNUSED_PAD src0_sel:WORD_1
	v_cvt_f32_f16_sdwa v65, v24 dst_sel:DWORD dst_unused:UNUSED_PAD src0_sel:WORD_1
	s_waitcnt vmcnt(11)
	v_cvt_f32_f16_e32 v60, v26
	v_cvt_f32_f16_e32 v62, v27
	v_cvt_f32_f16_sdwa v63, v27 dst_sel:DWORD dst_unused:UNUSED_PAD src0_sel:WORD_1
	v_cvt_f32_f16_sdwa v61, v26 dst_sel:DWORD dst_unused:UNUSED_PAD src0_sel:WORD_1
	s_waitcnt vmcnt(10)
	v_cvt_f32_f16_e32 v56, v28
	v_cvt_f32_f16_e32 v58, v29
	v_cvt_f32_f16_sdwa v59, v29 dst_sel:DWORD dst_unused:UNUSED_PAD src0_sel:WORD_1
	v_cvt_f32_f16_sdwa v57, v28 dst_sel:DWORD dst_unused:UNUSED_PAD src0_sel:WORD_1
	s_waitcnt vmcnt(9)
	v_cvt_f32_f16_e32 v52, v30
	v_cvt_f32_f16_e32 v54, v31
	v_cvt_f32_f16_sdwa v55, v31 dst_sel:DWORD dst_unused:UNUSED_PAD src0_sel:WORD_1
	v_cvt_f32_f16_sdwa v53, v30 dst_sel:DWORD dst_unused:UNUSED_PAD src0_sel:WORD_1
	s_waitcnt vmcnt(8)
	v_cvt_f32_f16_e32 v48, v32
	v_cvt_f32_f16_e32 v50, v33
	v_cvt_f32_f16_sdwa v51, v33 dst_sel:DWORD dst_unused:UNUSED_PAD src0_sel:WORD_1
	v_cvt_f32_f16_sdwa v49, v32 dst_sel:DWORD dst_unused:UNUSED_PAD src0_sel:WORD_1
	s_waitcnt vmcnt(7)
	v_cvt_f32_f16_e32 v44, v34
	v_cvt_f32_f16_e32 v46, v35
	v_cvt_f32_f16_sdwa v47, v35 dst_sel:DWORD dst_unused:UNUSED_PAD src0_sel:WORD_1
	v_cvt_f32_f16_sdwa v45, v34 dst_sel:DWORD dst_unused:UNUSED_PAD src0_sel:WORD_1
	s_waitcnt vmcnt(6)
	v_cvt_f32_f16_e32 v40, v36
	v_cvt_f32_f16_e32 v42, v37
	v_cvt_f32_f16_sdwa v43, v37 dst_sel:DWORD dst_unused:UNUSED_PAD src0_sel:WORD_1
	v_cvt_f32_f16_sdwa v41, v36 dst_sel:DWORD dst_unused:UNUSED_PAD src0_sel:WORD_1
	s_waitcnt vmcnt(5)
	v_cvt_f32_f16_e32 v36, v92
	v_cvt_f32_f16_e32 v38, v93
	v_cvt_f32_f16_sdwa v39, v93 dst_sel:DWORD dst_unused:UNUSED_PAD src0_sel:WORD_1
	v_cvt_f32_f16_sdwa v37, v92 dst_sel:DWORD dst_unused:UNUSED_PAD src0_sel:WORD_1
	s_waitcnt vmcnt(4)
	v_cvt_f32_f16_e32 v32, v104
	v_cvt_f32_f16_e32 v34, v105
	v_cvt_f32_f16_sdwa v35, v105 dst_sel:DWORD dst_unused:UNUSED_PAD src0_sel:WORD_1
	v_cvt_f32_f16_sdwa v33, v104 dst_sel:DWORD dst_unused:UNUSED_PAD src0_sel:WORD_1
	s_waitcnt vmcnt(3)
	v_cvt_f32_f16_e32 v28, v106
	v_cvt_f32_f16_e32 v30, v107
	v_cvt_f32_f16_sdwa v31, v107 dst_sel:DWORD dst_unused:UNUSED_PAD src0_sel:WORD_1
	v_cvt_f32_f16_sdwa v29, v106 dst_sel:DWORD dst_unused:UNUSED_PAD src0_sel:WORD_1
	s_waitcnt vmcnt(2)
	v_cvt_f32_f16_e32 v24, v108
	v_cvt_f32_f16_e32 v26, v109
	v_cvt_f32_f16_sdwa v27, v109 dst_sel:DWORD dst_unused:UNUSED_PAD src0_sel:WORD_1
	v_cvt_f32_f16_sdwa v25, v108 dst_sel:DWORD dst_unused:UNUSED_PAD src0_sel:WORD_1
	s_waitcnt vmcnt(1)
	v_cvt_f32_f16_e32 v20, v110
	v_cvt_f32_f16_e32 v22, v111
	v_cvt_f32_f16_sdwa v23, v111 dst_sel:DWORD dst_unused:UNUSED_PAD src0_sel:WORD_1
	v_cvt_f32_f16_sdwa v21, v110 dst_sel:DWORD dst_unused:UNUSED_PAD src0_sel:WORD_1
	s_waitcnt vmcnt(0)
	v_cvt_f32_f16_e32 v16, v112
	v_cvt_f32_f16_e32 v18, v113
	v_cvt_f32_f16_sdwa v19, v113 dst_sel:DWORD dst_unused:UNUSED_PAD src0_sel:WORD_1
	v_cvt_f32_f16_sdwa v17, v112 dst_sel:DWORD dst_unused:UNUSED_PAD src0_sel:WORD_1
	v_lshlrev_b64 v[92:93], 11, v[114:115]
	s_cbranch_execnz .LBB0_522
	s_branch .LBB0_526
.LBB0_525:
.LBB0_526:
	v_add_co_u32_e32 v16, vcc, 0xffffd000, v88
	s_mov_b64 s[0:1], 0x800
	s_nop 0
	v_addc_co_u32_e32 v17, vcc, -1, v89, vcc
	global_load_dwordx4 v[76:79], v[16:17], off offset:-3072 nt
	global_load_dwordx4 v[72:75], v[16:17], off offset:-2048 nt
	global_load_dwordx4 v[68:71], v[16:17], off offset:-1024 nt
	global_load_dwordx4 v[64:67], v[16:17], off nt
	v_add_co_u32_e32 v16, vcc, 0xffffe000, v88
	v_lshl_add_u64 v[96:97], v[86:87], 0, s[0:1]
	s_nop 0
	v_addc_co_u32_e32 v17, vcc, -1, v89, vcc
	global_load_dwordx4 v[60:63], v[16:17], off offset:-3072 nt
	global_load_dwordx4 v[56:59], v[16:17], off offset:-2048 nt
	global_load_dwordx4 v[52:55], v[16:17], off offset:-1024 nt
	global_load_dwordx4 v[48:51], v[16:17], off nt
	v_add_co_u32_e32 v16, vcc, 0xfffff000, v88
	s_mov_b64 s[0:1], 0x1000
	s_nop 0
	v_addc_co_u32_e32 v17, vcc, -1, v89, vcc
	global_load_dwordx4 v[44:47], v[16:17], off offset:-3072 nt
	global_load_dwordx4 v[40:43], v[16:17], off offset:-2048 nt
	global_load_dwordx4 v[36:39], v[16:17], off offset:-1024 nt
	global_load_dwordx4 v[32:35], v[88:89], off offset:-4096 nt
	global_load_dwordx4 v[28:31], v[88:89], off offset:-3072 nt
	global_load_dwordx4 v[24:27], v[88:89], off offset:-2048 nt
	global_load_dwordx4 v[20:23], v[88:89], off offset:-1024 nt
	s_nop 0
	global_load_dwordx4 v[16:19], v[88:89], off nt
	v_lshl_add_u64 v[94:95], v[86:87], 0, s[0:1]
	s_mov_b64 s[0:1], 0x1800
	v_lshl_add_u64 v[92:93], v[86:87], 0, s[0:1]
	s_branch .LBB0_522
